# stack2 + one static s_setprio 1 for waves 4-7 over the attention phase (reset after it)
# speedup vs baseline: 1.0021x; 1.0021x over previous
.LBB8_541:
	v_writelane_b32 v254, s26, 59
	s_cmp_lt_i32 s92, 5
	s_cselect_b64 s[4:5], -1, 0
	v_writelane_b32 v254, s27, 60
	s_nop 0
	v_readlane_b32 s6, v254, 2
	v_readlane_b32 s7, v254, 3
	s_add_u32 s26, s6, 0xc0000
	s_addc_u32 s27, s7, 0
	s_add_u32 s70, s6, 0x4800000
	s_addc_u32 s71, s7, 0
	s_and_b64 s[0:1], s[4:5], s[0:1]
	v_writelane_b32 v254, s0, 61
	s_andn2_b64 vcc, exec, s[0:1]
	s_nop 0
	v_writelane_b32 v254, s1, 62
	s_cbranch_vccnz .LBB8_774
	s_cmpk_lt_u32 s96, 0x100
	s_cbranch_scc1 .Lq_p4_noprio
	s_setprio 1
.Lq_p4_noprio:
	s_sub_i32 s0, 0xa03f, s67
	s_ashr_i32 s1, s0, 31
	s_lshr_b32 s1, s1, 26
	v_writelane_b32 v254, s84, 63
	s_add_i32 s1, s0, s1
	s_ashr_i32 s4, s1, 6
	v_readlane_b32 s6, v254, 2
	v_readlane_b32 s7, v254, 3
	s_add_u32 s1, s6, 0x6800000
	s_waitcnt vmcnt(0) lgkmcnt(0)
	v_mbcnt_lo_u32_b32 v0, -1, 0
	v_mbcnt_hi_u32_b32 v0, -1, v0
	v_writelane_b32 v255, s1, 0
	s_addc_u32 s1, s7, 0
	v_writelane_b32 v255, s1, 1
	s_min_i32 s1, s4, 0x200
	s_add_i32 s38, s4, 0x400
	s_cmp_gt_i32 s0, 0x803f
	s_mul_i32 s56, s1, 3
	v_writelane_b32 v255, s4, 2
	s_cselect_b64 s[0:1], -1, 0
	v_writelane_b32 v255, s0, 3
	v_readlane_b32 s4, v254, 4
	v_sub_u32_e32 v0, 0, v0
	v_writelane_b32 v255, s1, 4
	s_lshl_b32 s0, s4, 5
	v_writelane_b32 v255, s0, 5
	s_lshl_b32 s0, s4, 8
	s_add_i32 s1, 0, 0x10000
	s_add_i32 s94, s1, s0
	s_lshl_b32 s0, s4, 13
	s_add_i32 s57, s0, 0
	s_lshl_b32 s0, s4, 3
	v_writelane_b32 v255, s0, 6
	s_lshl_b32 s0, s96, 2
	s_add_i32 s1, s1, s0
	s_add_u32 s6, s6, 0x120000
	v_writelane_b32 v255, s1, 7
	s_addc_u32 s7, s7, 0
	v_writelane_b32 v255, s6, 8
	s_add_i32 s0, s0, 0
	s_add_i32 s0, s0, 0x10800
	v_writelane_b32 v255, s7, 9
	v_writelane_b32 v255, s0, 10
	s_lshl_b32 s0, s4, 2
	s_add_i32 s0, s0, 0
	s_add_i32 s0, s0, 0x21900
	v_writelane_b32 v255, s0, 11
	s_mul_i32 s0, s4, 0x2100
	s_mov_b32 s4, 0x3fb8aa3b
	v_writelane_b32 v255, s4, 12
	s_add_i32 s95, s57, s0
	v_cmp_eq_u32_e64 s[0:1], s96, v0
	v_writelane_b32 v255, s5, 13
	s_add_i32 s4, 0, 0x11800
	v_writelane_b32 v255, s4, 14
	s_add_i32 s4, 0, 0x4000
	v_writelane_b32 v255, s4, 15
	s_add_i32 s4, 0, 0x19800
	v_writelane_b32 v255, s4, 16
	s_add_i32 s4, 0, 0x21910
	v_writelane_b32 v255, s4, 17
	v_writelane_b32 v255, s56, 18
	s_add_i32 s33, 0, 0x21940
	v_mbcnt_lo_u32_b32 v0, -1, 0
	v_writelane_b32 v255, s57, 19
	s_mov_b64 s[62:63], s[88:89]
	s_movk_i32 s93, 0x200
	s_mov_b32 s89, 0
	s_mov_b32 s39, 0x10000
	v_mov_b32_e32 v1, 0
	v_mov_b32_e32 v168, s33
	v_mov_b32_e32 v169, 0x358637bd
	s_mov_b32 s86, 0xf800000
	v_mov_b32_e32 v170, 0x260
	s_mov_b32 s92, 0x3e0293ee
	s_movk_i32 s87, 0x4d00
	s_mov_b32 s58, 0x41000000
	s_mov_b32 s59, 0x20000
	v_mbcnt_hi_u32_b32 v171, -1, v0
	v_mov_b32_e32 v172, 0x268000
	v_mov_b32_e32 v173, 0xff800000
	v_bfrev_b32_e32 v174, 1
	v_mov_b32_e32 v175, 0x7f800000
	v_writelane_b32 v255, s33, 20
	s_branch .LBB8_546

.LBB8_774:
	s_setprio 0
	v_readlane_b32 s4, v254, 47
	v_readlane_b32 s5, v254, 48
	s_cmp_gt_i32 s5, 5
	v_readlane_b32 s4, v254, 61
	s_cselect_b64 s[0:1], -1, 0
	v_readlane_b32 s5, v254, 62
	s_and_b64 s[4:5], s[4:5], s[0:1]
	v_readlane_b32 s92, v254, 45
	s_andn2_b64 vcc, exec, s[4:5]
	v_readlane_b32 s93, v254, 46
	v_readlane_b32 s6, v254, 49
	v_readlane_b32 s7, v254, 50
	s_cbranch_vccnz .LBB8_828
	s_waitcnt vmcnt(0) lgkmcnt(0)
	v_mbcnt_lo_u32_b32 v0, -1, 0
	v_mbcnt_hi_u32_b32 v0, -1, v0
	s_waitcnt vmcnt(0)
	s_nop 0
	v_sub_u32_e32 v0, 0, v0
	v_cmp_eq_u32_e32 vcc, s96, v0
	s_barrier
	s_and_saveexec_b64 s[4:5], vcc
	s_cbranch_execz .LBB8_827
	s_add_i32 s6, 0, 0x25c20
	v_mov_b32_e32 v0, s6
	s_waitcnt vmcnt(0) expcnt(0) lgkmcnt(0)
	ds_read_b32 v2, v0
	s_add_i32 s6, 0, 0x25c24
	v_mov_b32_e32 v0, s6
	ds_read_b32 v0, v0
	s_waitcnt lgkmcnt(1)
	v_cmp_ne_u32_e32 vcc, 0, v2
	s_cbranch_vccnz .LBB8_791
	v_readlane_b32 s6, v254, 0
	v_readlane_b32 s7, v254, 1
	s_load_dwordx2 s[10:11], s[6:7], 0x4
	s_add_u32 s6, s30, 0x1000
	s_addc_u32 s7, s31, 0
	s_add_u32 s8, s30, 0x1100
	s_addc_u32 s9, s31, 0
	s_waitcnt lgkmcnt(0)
	s_mul_i32 s20, s10, s3
	s_add_u32 s10, s30, 0x1200
	s_mul_i32 s20, s20, s11
	s_addc_u32 s11, s31, 0
	s_add_u32 s12, s30, 0x1300
	s_addc_u32 s13, s31, 0
	s_mov_b32 s21, 1
	v_mov_b32_e32 v16, 0
	s_branch .LBB8_779
